# v3 + GEMM2 epilogue row sums of squares via DPP instead of ds_bpermute (bit-identical)
# speedup vs baseline: 1.0015x; 1.0015x over previous
.LBB0_406:
	v_mul_f32_e32 v64, v73, v73
	v_mul_f32_e32 v65, v69, v69
	v_fmac_f32_e32 v64, v72, v72
	v_fmac_f32_e32 v65, v68, v68
	v_add_f32_e32 v64, v64, v65
	v_mul_f32_e32 v65, v75, v75
	v_mul_f32_e32 v66, v71, v71
	v_fmac_f32_e32 v65, v74, v74
	v_fmac_f32_e32 v66, v70, v70
	v_add_f32_e32 v65, v65, v66
	v_add_f32_e32 v64, v64, v65
	s_lshl_b32 s18, s18, 1
	s_ashr_i32 s19, s18, 31
	s_lshl_b64 s[18:19], s[18:19], 2
	s_add_u32 s18, s57, s18
	s_waitcnt lgkmcnt(0)
	s_nop 0
	v_add_f32_dpp v64, v64, v64 quad_perm:[1,0,3,2] row_mask:0xf bank_mask:0xf
	v_cmp_eq_u32_e64 s[40:41], 0, v159
	s_addc_u32 s19, s58, s19
	s_waitcnt lgkmcnt(0)
	s_nop 0
	v_add_f32_dpp v66, v64, v64 quad_perm:[2,3,0,1] row_mask:0xf bank_mask:0xf
	s_nop 1
	v_add_f32_dpp v67, v66, v66 row_half_mirror row_mask:0xf bank_mask:0xf
	v_add_u32_e32 v64, s28, v140
	v_ashrrev_i32_e32 v65, 31, v64
	s_and_saveexec_b64 s[42:43], s[40:41]
	s_cbranch_execz .LBB0_408
	s_waitcnt lgkmcnt(0)
	v_mov_b32_e32 v76, v67
	v_lshlrev_b64 v[66:67], 6, v[64:65]
	v_lshl_add_u64 v[66:67], s[18:19], 0, v[66:67]
	global_store_dword v[66:67], v76, off sc1

.LBB0_414:
	v_mul_f32_e32 v64, v71, v71
	v_mul_f32_e32 v65, v75, v75
	v_fmac_f32_e32 v64, v70, v70
	v_fmac_f32_e32 v65, v74, v74
	v_add_f32_e32 v64, v64, v65
	v_mul_f32_e32 v65, v73, v73
	v_mul_f32_e32 v66, v77, v77
	v_fmac_f32_e32 v65, v72, v72
	v_fmac_f32_e32 v66, v76, v76
	v_add_f32_e32 v65, v65, v66
	v_add_f32_e32 v64, v64, v65
	s_waitcnt lgkmcnt(0)
	s_nop 0
	v_add_f32_dpp v64, v64, v64 quad_perm:[1,0,3,2] row_mask:0xf bank_mask:0xf
	s_waitcnt lgkmcnt(0)
	s_nop 0
	v_add_f32_dpp v65, v64, v64 quad_perm:[2,3,0,1] row_mask:0xf bank_mask:0xf
	s_nop 1
	v_add_f32_dpp v66, v65, v65 row_half_mirror row_mask:0xf bank_mask:0xf
	v_add_u32_e32 v64, s28, v84
	s_and_saveexec_b64 s[34:35], s[40:41]
	s_cbranch_execz .LBB0_416
	s_waitcnt lgkmcnt(0)
	v_mov_b32_e32 v78, v66
	v_ashrrev_i32_e32 v65, 31, v64
	v_lshlrev_b64 v[66:67], 6, v[64:65]
	v_lshl_add_u64 v[66:67], s[18:19], 0, v[66:67]
	global_store_dword v[66:67], v78, off sc1

.LBB0_422:
	v_mul_f32_e32 v56, v65, v65
	v_mul_f32_e32 v57, v67, v67
	v_fmac_f32_e32 v56, v64, v64
	v_fmac_f32_e32 v57, v66, v66
	v_add_f32_e32 v56, v56, v57
	v_mul_f32_e32 v57, v63, v63
	v_mul_f32_e32 v58, v71, v71
	v_fmac_f32_e32 v57, v62, v62
	v_fmac_f32_e32 v58, v70, v70
	v_add_f32_e32 v57, v57, v58
	v_add_f32_e32 v56, v56, v57
	s_waitcnt lgkmcnt(0)
	s_nop 0
	v_add_f32_dpp v56, v56, v56 quad_perm:[1,0,3,2] row_mask:0xf bank_mask:0xf
	s_waitcnt lgkmcnt(0)
	s_nop 0
	v_add_f32_dpp v57, v56, v56 quad_perm:[2,3,0,1] row_mask:0xf bank_mask:0xf
	s_nop 1
	v_add_f32_dpp v58, v57, v57 row_half_mirror row_mask:0xf bank_mask:0xf
	v_add_u32_e32 v56, s28, v86
	s_and_saveexec_b64 s[34:35], s[40:41]
	s_cbranch_execz .LBB0_424
	s_waitcnt lgkmcnt(0)
	v_mov_b32_e32 v72, v58
	v_ashrrev_i32_e32 v57, 31, v56
	v_lshlrev_b64 v[58:59], 6, v[56:57]
	v_lshl_add_u64 v[58:59], s[18:19], 0, v[58:59]
	global_store_dword v[58:59], v72, off sc1

.LBB0_430:
	v_mul_f32_e32 v48, v57, v57
	v_mul_f32_e32 v49, v59, v59
	v_fmac_f32_e32 v48, v56, v56
	v_fmac_f32_e32 v49, v58, v58
	v_add_f32_e32 v48, v48, v49
	v_mul_f32_e32 v49, v55, v55
	v_mul_f32_e32 v50, v63, v63
	v_fmac_f32_e32 v49, v54, v54
	v_fmac_f32_e32 v50, v62, v62
	v_add_f32_e32 v49, v49, v50
	v_add_f32_e32 v48, v48, v49
	s_waitcnt lgkmcnt(0)
	s_nop 0
	v_add_f32_dpp v48, v48, v48 quad_perm:[1,0,3,2] row_mask:0xf bank_mask:0xf
	s_waitcnt lgkmcnt(0)
	s_nop 0
	v_add_f32_dpp v49, v48, v48 quad_perm:[2,3,0,1] row_mask:0xf bank_mask:0xf
	s_nop 1
	v_add_f32_dpp v50, v49, v49 row_half_mirror row_mask:0xf bank_mask:0xf
	v_add_u32_e32 v48, s28, v88
	s_and_saveexec_b64 s[34:35], s[40:41]
	s_cbranch_execz .LBB0_432
	s_waitcnt lgkmcnt(0)
	v_mov_b32_e32 v64, v50
	v_ashrrev_i32_e32 v49, 31, v48
	v_lshlrev_b64 v[50:51], 6, v[48:49]
	v_lshl_add_u64 v[50:51], s[18:19], 0, v[50:51]
	global_store_dword v[50:51], v64, off sc1

.LBB0_446:
	v_mul_f32_e32 v16, v21, v21
	v_mul_f32_e32 v17, v25, v25
	v_fmac_f32_e32 v16, v20, v20
	v_fmac_f32_e32 v17, v24, v24
	v_add_f32_e32 v16, v16, v17
	v_mul_f32_e32 v17, v23, v23
	v_mul_f32_e32 v18, v27, v27
	v_fmac_f32_e32 v17, v22, v22
	v_fmac_f32_e32 v18, v26, v26
	v_add_f32_e32 v17, v17, v18
	v_add_f32_e32 v16, v16, v17
	s_waitcnt lgkmcnt(0)
	s_nop 0
	v_add_f32_dpp v16, v16, v16 quad_perm:[1,0,3,2] row_mask:0xf bank_mask:0xf
	s_waitcnt lgkmcnt(0)
	s_nop 0
	v_add_f32_dpp v18, v16, v16 quad_perm:[2,3,0,1] row_mask:0xf bank_mask:0xf
	s_nop 1
	v_add_f32_dpp v19, v18, v18 row_half_mirror row_mask:0xf bank_mask:0xf
	v_add_u32_e32 v16, s34, v140
	v_ashrrev_i32_e32 v17, 31, v16
	s_and_saveexec_b64 s[16:17], s[40:41]
	s_cbranch_execz .LBB0_448
	s_waitcnt lgkmcnt(0)
	v_mov_b32_e32 v28, v19
	v_lshlrev_b64 v[18:19], 6, v[16:17]
	v_lshl_add_u64 v[18:19], s[18:19], 0, v[18:19]
	global_store_dword v[18:19], v28, off sc1

.LBB0_454:
	v_mul_f32_e32 v16, v21, v21
	v_mul_f32_e32 v17, v25, v25
	v_fmac_f32_e32 v16, v20, v20
	v_fmac_f32_e32 v17, v24, v24
	v_add_f32_e32 v16, v16, v17
	v_mul_f32_e32 v17, v23, v23
	v_mul_f32_e32 v18, v27, v27
	v_fmac_f32_e32 v17, v22, v22
	v_fmac_f32_e32 v18, v26, v26
	v_add_f32_e32 v17, v17, v18
	v_add_f32_e32 v16, v16, v17
	s_waitcnt lgkmcnt(0)
	s_nop 0
	v_add_f32_dpp v16, v16, v16 quad_perm:[1,0,3,2] row_mask:0xf bank_mask:0xf
	s_waitcnt lgkmcnt(0)
	s_nop 0
	v_add_f32_dpp v17, v16, v16 quad_perm:[2,3,0,1] row_mask:0xf bank_mask:0xf
	s_nop 1
	v_add_f32_dpp v18, v17, v17 row_half_mirror row_mask:0xf bank_mask:0xf
	v_add_u32_e32 v16, s34, v84
	s_and_saveexec_b64 s[16:17], s[40:41]
	s_cbranch_execz .LBB0_456
	s_waitcnt lgkmcnt(0)
	v_mov_b32_e32 v28, v18
	v_ashrrev_i32_e32 v17, 31, v16
	v_lshlrev_b64 v[18:19], 6, v[16:17]
	v_lshl_add_u64 v[18:19], s[18:19], 0, v[18:19]
	global_store_dword v[18:19], v28, off sc1

.LBB0_462:
	v_mul_f32_e32 v16, v21, v21
	v_mul_f32_e32 v17, v25, v25
	v_fmac_f32_e32 v16, v20, v20
	v_fmac_f32_e32 v17, v24, v24
	v_add_f32_e32 v16, v16, v17
	v_mul_f32_e32 v17, v23, v23
	v_mul_f32_e32 v18, v27, v27
	v_fmac_f32_e32 v17, v22, v22
	v_fmac_f32_e32 v18, v26, v26
	v_add_f32_e32 v17, v17, v18
	v_add_f32_e32 v16, v16, v17
	s_waitcnt lgkmcnt(0)
	s_nop 0
	v_add_f32_dpp v16, v16, v16 quad_perm:[1,0,3,2] row_mask:0xf bank_mask:0xf
	s_waitcnt lgkmcnt(0)
	s_nop 0
	v_add_f32_dpp v17, v16, v16 quad_perm:[2,3,0,1] row_mask:0xf bank_mask:0xf
	s_nop 1
	v_add_f32_dpp v18, v17, v17 row_half_mirror row_mask:0xf bank_mask:0xf
	v_add_u32_e32 v16, s34, v86
	s_and_saveexec_b64 s[16:17], s[40:41]
	s_cbranch_execz .LBB0_464
	s_waitcnt lgkmcnt(0)
	v_mov_b32_e32 v28, v18
	v_ashrrev_i32_e32 v17, 31, v16
	v_lshlrev_b64 v[18:19], 6, v[16:17]
	v_lshl_add_u64 v[18:19], s[18:19], 0, v[18:19]
	global_store_dword v[18:19], v28, off sc1

.LBB0_470:
	v_mul_f32_e32 v8, v13, v13
	v_mul_f32_e32 v9, v17, v17
	v_fmac_f32_e32 v8, v12, v12
	v_fmac_f32_e32 v9, v16, v16
	v_add_f32_e32 v8, v8, v9
	v_mul_f32_e32 v9, v15, v15
	v_mul_f32_e32 v10, v19, v19
	v_fmac_f32_e32 v9, v14, v14
	v_fmac_f32_e32 v10, v18, v18
	v_add_f32_e32 v9, v9, v10
	v_add_f32_e32 v8, v8, v9
	s_waitcnt lgkmcnt(0)
	s_nop 0
	v_add_f32_dpp v8, v8, v8 quad_perm:[1,0,3,2] row_mask:0xf bank_mask:0xf
	s_waitcnt lgkmcnt(0)
	s_nop 0
	v_add_f32_dpp v9, v8, v8 quad_perm:[2,3,0,1] row_mask:0xf bank_mask:0xf
	s_nop 1
	v_add_f32_dpp v10, v9, v9 row_half_mirror row_mask:0xf bank_mask:0xf
	v_add_u32_e32 v8, s34, v88
	s_and_saveexec_b64 s[16:17], s[40:41]
	s_cbranch_execz .LBB0_472
	s_waitcnt lgkmcnt(0)
	v_mov_b32_e32 v20, v10
	v_ashrrev_i32_e32 v9, 31, v8
	v_lshlrev_b64 v[10:11], 6, v[8:9]
	v_lshl_add_u64 v[10:11], s[18:19], 0, v[10:11]
	global_store_dword v[10:11], v20, off sc1
